# GEMM phase prologues (14 sites): K-tile 1 LDS-DMA issued together with K-tile 0, first wait vmcnt(2)->vmcnt(8)
# baseline (speedup 1.0000x reference)
.LBB0_287:
	s_add_u32 s10, s8, 0x50800000
	s_addc_u32 s11, s9, 0
	s_add_u32 s4, s34, 0x80
	s_addc_u32 s5, s35, 0
	s_add_i32 m0, s13, 0x18000
	s_nop 0
	global_load_lds_dwordx4 v131, s[4:5]
	s_add_i32 m0, s13, 0x1a000
	s_nop 0
	global_load_lds_dwordx4 v133, s[4:5]
	s_add_u32 s4, s30, 0x80
	s_addc_u32 s5, s31, 0
	s_add_i32 s48, s13, 0x8000
	s_mov_b32 m0, s48
	s_add_i32 s49, s13, 0xa000
	global_load_lds_dwordx4 v130, s[4:5]
	s_mov_b32 m0, s49
	s_nop 0
	global_load_lds_dwordx4 v132, s[4:5]
	s_add_u32 s4, s34, 0x80080
	s_addc_u32 s5, s35, 0
	s_add_i32 m0, s13, 0x1c000
	s_nop 0
	global_load_lds_dwordx4 v131, s[4:5]
	s_add_i32 m0, s13, 0x1e000
	s_nop 0
	global_load_lds_dwordx4 v133, s[4:5]
	s_movk_i32 s4, 0x3c0
	s_waitcnt vmcnt(8)
	s_barrier
	v_and_b32_e32 v1, 15, v0
	v_or_b32_e32 v2, s64, v1
	v_lshlrev_b32_e32 v4, 6, v2
	v_and_b32_e32 v5, 48, v0
	v_ashrrev_i32_e32 v3, 6, v0
	v_lshlrev_b32_e32 v2, 2, v2
	v_and_or_b32 v4, v4, s4, v5
	v_readlane_b32 s4, v254, 19
	v_and_b32_e32 v2, 32, v2
	v_lshlrev_b32_e32 v0, 2, v0
	v_lshl_add_u32 v6, v3, 10, s4
	v_readlane_b32 s4, v254, 21
	s_waitcnt vmcnt(6)
	v_bitop3_b32 v2, v4, v6, v2 bitop3:0xde
	v_lshl_or_b32 v1, v1, 6, v5
	v_add_lshl_u32 v3, v3, s4, 10
	v_and_b32_e32 v0, 32, v0
	v_bitop3_b32 v134, v1, v3, v0 bitop3:0xde
	s_add_i32 s65, s3, s16
	v_add_u32_e32 v135, 0, v2
	s_barrier
	s_branch .LBB0_290

.LBB0_308:
	s_add_u32 s8, s8, 0x54800000
	s_addc_u32 s9, s9, 0
	s_add_u32 s4, s36, 0x80
	s_addc_u32 s5, s37, 0
	s_add_i32 m0, s25, 0x18000
	s_nop 0
	global_load_lds_dwordx4 v132, s[4:5]
	s_add_i32 m0, s25, 0x1a000
	s_nop 0
	global_load_lds_dwordx4 v130, s[4:5]
	s_add_u32 s4, s30, 0x80
	s_addc_u32 s5, s31, 0
	s_add_i32 s48, s25, 0x8000
	s_mov_b32 m0, s48
	s_add_i32 s49, s25, 0xa000
	global_load_lds_dwordx4 v133, s[4:5]
	s_mov_b32 m0, s49
	s_nop 0
	global_load_lds_dwordx4 v131, s[4:5]
	s_add_u32 s4, s36, 0x80080
	s_addc_u32 s5, s37, 0
	s_add_i32 m0, s25, 0x1c000
	s_nop 0
	global_load_lds_dwordx4 v132, s[4:5]
	s_add_i32 m0, s25, 0x1e000
	s_nop 0
	global_load_lds_dwordx4 v130, s[4:5]
	s_movk_i32 s4, 0x3c0
	s_waitcnt vmcnt(8)
	s_barrier
	v_and_b32_e32 v1, 15, v0
	v_or_b32_e32 v2, s64, v1
	v_lshlrev_b32_e32 v4, 6, v2
	v_and_b32_e32 v5, 48, v0
	v_ashrrev_i32_e32 v3, 6, v0
	v_lshlrev_b32_e32 v2, 2, v2
	v_and_or_b32 v4, v4, s4, v5
	v_readlane_b32 s4, v254, 19
	v_and_b32_e32 v2, 32, v2
	v_lshlrev_b32_e32 v0, 2, v0
	v_lshl_add_u32 v6, v3, 10, s4
	v_readlane_b32 s4, v254, 21
	s_waitcnt vmcnt(6)
	v_bitop3_b32 v2, v4, v6, v2 bitop3:0xde
	v_lshl_or_b32 v1, v1, 6, v5
	v_add_lshl_u32 v3, v3, s4, 10
	v_and_b32_e32 v0, 32, v0
	v_bitop3_b32 v134, v1, v3, v0 bitop3:0xde
	s_add_i32 s65, s3, s10
	v_add_u32_e32 v135, 0, v2
	s_barrier
	s_branch .LBB0_311

.LBB0_366:
	s_add_u32 s48, s8, 0x56400000
	s_addc_u32 s49, s9, 0
	s_add_u32 s4, s28, 0x80
	s_addc_u32 s5, s29, 0
	s_add_i32 m0, s23, 0x18000
	s_nop 0
	global_load_lds_dwordx4 v132, s[4:5]
	s_add_i32 m0, s23, 0x1a000
	s_nop 0
	global_load_lds_dwordx4 v130, s[4:5]
	s_add_u32 s4, s30, 0x80
	s_addc_u32 s5, s31, 0
	s_add_i32 s56, s23, 0x8000
	s_mov_b32 m0, s56
	s_add_i32 s57, s23, 0xa000
	global_load_lds_dwordx4 v133, s[4:5]
	s_mov_b32 m0, s57
	s_nop 0
	global_load_lds_dwordx4 v131, s[4:5]
	s_add_u32 s4, s12, 0x80
	s_addc_u32 s5, s13, 0
	s_add_i32 m0, s23, 0x1c000
	s_nop 0
	global_load_lds_dwordx4 v132, s[4:5]
	s_add_i32 m0, s23, 0x1e000
	s_nop 0
	global_load_lds_dwordx4 v130, s[4:5]
	s_movk_i32 s4, 0x3c0
	s_waitcnt vmcnt(8)
	s_barrier
	v_and_b32_e32 v1, 15, v0
	v_or_b32_e32 v2, s64, v1
	v_lshlrev_b32_e32 v4, 6, v2
	v_and_b32_e32 v5, 48, v0
	v_ashrrev_i32_e32 v3, 6, v0
	v_lshlrev_b32_e32 v2, 2, v2
	v_and_or_b32 v4, v4, s4, v5
	v_readlane_b32 s4, v254, 19
	v_and_b32_e32 v2, 32, v2
	v_lshlrev_b32_e32 v0, 2, v0
	v_lshl_add_u32 v6, v3, 10, s4
	v_readlane_b32 s4, v254, 21
	s_waitcnt vmcnt(6)
	v_bitop3_b32 v2, v4, v6, v2 bitop3:0xde
	v_lshl_or_b32 v1, v1, 6, v5
	v_add_lshl_u32 v3, v3, s4, 10
	v_and_b32_e32 v0, 32, v0
	v_bitop3_b32 v134, v1, v3, v0 bitop3:0xde
	s_mov_b32 s65, 0
	v_add_u32_e32 v135, 0, v2
	s_barrier
	s_branch .LBB0_369

.LBB0_391:
	s_add_u32 s10, s10, 0x3c800000
	s_addc_u32 s11, s11, 0
	s_add_u32 s4, s26, 0x80
	s_addc_u32 s5, s27, 0
	s_add_i32 m0, s25, 0x18000
	s_nop 0
	global_load_lds_dwordx4 v132, s[4:5]
	s_add_i32 m0, s25, 0x1a000
	s_nop 0
	global_load_lds_dwordx4 v130, s[4:5]
	s_add_u32 s4, s8, 0x80
	s_addc_u32 s5, s9, 0
	s_add_i32 s44, s25, 0x8000
	s_mov_b32 m0, s44
	s_add_i32 s46, s25, 0xa000
	global_load_lds_dwordx4 v133, s[4:5]
	s_mov_b32 m0, s46
	s_nop 0
	global_load_lds_dwordx4 v131, s[4:5]
	s_add_u32 s4, s12, 0x80
	s_addc_u32 s5, s13, 0
	s_add_i32 m0, s25, 0x1c000
	s_nop 0
	global_load_lds_dwordx4 v132, s[4:5]
	s_add_i32 m0, s25, 0x1e000
	s_nop 0
	global_load_lds_dwordx4 v130, s[4:5]
	s_movk_i32 s4, 0x3c0
	s_waitcnt vmcnt(8)
	s_barrier
	v_and_b32_e32 v1, 15, v0
	v_or_b32_e32 v2, s64, v1
	v_lshlrev_b32_e32 v4, 6, v2
	v_and_b32_e32 v5, 48, v0
	v_ashrrev_i32_e32 v3, 6, v0
	v_lshlrev_b32_e32 v2, 2, v2
	v_and_or_b32 v4, v4, s4, v5
	v_readlane_b32 s4, v254, 19
	v_and_b32_e32 v2, 32, v2
	v_lshlrev_b32_e32 v0, 2, v0
	v_lshl_add_u32 v6, v3, 10, s4
	v_readlane_b32 s4, v254, 21
	s_waitcnt vmcnt(6)
	v_bitop3_b32 v2, v4, v6, v2 bitop3:0xde
	v_lshl_or_b32 v1, v1, 6, v5
	v_add_lshl_u32 v3, v3, s4, 10
	v_and_b32_e32 v0, 32, v0
	v_bitop3_b32 v134, v1, v3, v0 bitop3:0xde
	s_mov_b32 s4, 0
	v_add_u32_e32 v135, 0, v2
	s_mov_b64 s[28:29], s[8:9]
	s_mov_b32 s47, 0
	s_barrier
	s_branch .LBB0_394

.LBB0_517:
	s_add_u32 s14, s14, 0x15300000
	s_addc_u32 s15, s15, 0
	s_lshl_b32 s44, s85, 12
	s_lshl_b64 s[4:5], s[44:45], 2
	s_add_u32 s4, s22, s4
	s_addc_u32 s5, s23, s5
	s_add_u32 s44, s4, 0x10000
	s_addc_u32 s49, s5, 0
	s_add_u32 s4, s16, 0x8000
	s_addc_u32 s5, s17, 0
	v_writelane_b32 v255, s4, 14
	s_add_u32 s20, s20, 0x28100000
	s_addc_u32 s21, s21, 0
	v_writelane_b32 v255, s5, 15
	v_readlane_b32 s16, v254, 62
	v_readlane_b32 s4, v255, 3
	v_readlane_b32 s17, v254, 63
	s_add_u32 s22, s16, 0x4000
	v_readlane_b32 s5, v255, 4
	s_addc_u32 s23, s17, 0
	s_lshl_b64 s[4:5], s[4:5], 2
	s_add_u32 s24, s24, s4
	s_addc_u32 s25, s25, s5
	s_add_u32 s26, s16, 0x8000
	s_addc_u32 s27, s17, 0
	s_add_u32 s28, s16, 0x6000
	s_addc_u32 s29, s17, 0
	s_add_u32 s30, s30, 0x2d100000
	s_addc_u32 s31, s31, 0
	s_add_u32 s4, s8, 0x80
	s_addc_u32 s5, s9, 0
	s_add_i32 m0, s89, 0x18000
	s_nop 0
	global_load_lds_dwordx4 v181, s[4:5]
	s_add_i32 m0, s89, 0x1a000
	s_nop 0
	global_load_lds_dwordx4 v183, s[4:5]
	s_add_u32 s4, s12, 0x80
	s_addc_u32 s5, s13, 0
	s_add_i32 s46, s89, 0x8000
	s_mov_b32 m0, s46
	s_add_i32 s70, s89, 0xa000
	global_load_lds_dwordx4 v179, s[4:5]
	s_mov_b32 m0, s70
	s_nop 0
	global_load_lds_dwordx4 v182, s[4:5]
	s_add_u32 s4, s34, 0x80
	s_addc_u32 s5, s35, 0
	s_add_i32 m0, s89, 0x1c000
	s_nop 0
	global_load_lds_dwordx4 v181, s[4:5]
	s_add_i32 m0, s89, 0x1e000
	s_nop 0
	global_load_lds_dwordx4 v183, s[4:5]
	s_movk_i32 s4, 0x3c0
	s_waitcnt vmcnt(8)
	s_barrier
	v_and_b32_e32 v2, 15, v0
	v_or_b32_e32 v3, s64, v2
	v_lshlrev_b32_e32 v4, 6, v3
	v_and_b32_e32 v5, 48, v0
	v_and_b32_e32 v1, 0xfffffc00, v1
	v_lshlrev_b32_e32 v3, 2, v3
	v_and_or_b32 v4, v4, s4, v5
	v_readlane_b32 s4, v254, 19
	v_and_b32_e32 v3, 32, v3
	v_lshlrev_b32_e32 v0, 2, v0
	v_add_u32_e32 v6, s4, v1
	v_readlane_b32 s4, v254, 26
	s_waitcnt vmcnt(6)
	v_bitop3_b32 v3, v4, v6, v3 bitop3:0xde
	v_lshl_or_b32 v2, v2, 6, v5
	v_add_u32_e32 v1, s4, v1
	v_and_b32_e32 v0, 32, v0
	v_bitop3_b32 v184, v2, v1, v0 bitop3:0xde
	s_mov_b32 s71, 0
	v_add_u32_e32 v185, 0, v3
	s_barrier
	s_branch .LBB0_520

.LBB0_594:
	s_add_u32 s10, s8, 0x54c00000
	s_addc_u32 s11, s9, 0
	v_readlane_b32 s4, v255, 1
	v_readlane_b32 s5, v255, 2
	s_add_u32 s12, s4, 0x4000
	s_addc_u32 s13, s5, 0
	s_add_u32 s4, s34, 0x80
	s_addc_u32 s5, s35, 0
	s_add_i32 m0, s27, 0x18000
	s_nop 0
	global_load_lds_dwordx4 v152, s[4:5]
	s_add_i32 m0, s27, 0x1a000
	s_nop 0
	global_load_lds_dwordx4 v153, s[4:5]
	s_add_u32 s4, s36, 0x80
	s_addc_u32 s5, s37, 0
	s_add_i32 s49, s27, 0x8000
	s_mov_b32 m0, s49
	s_add_i32 s56, s27, 0xa000
	global_load_lds_dwordx4 v151, s[4:5]
	s_mov_b32 m0, s56
	s_nop 0
	global_load_lds_dwordx4 v150, s[4:5]
	s_add_u32 s4, s14, 0x80
	s_addc_u32 s5, s15, 0
	s_add_i32 m0, s27, 0x1c000
	s_nop 0
	global_load_lds_dwordx4 v152, s[4:5]
	s_add_i32 m0, s27, 0x1e000
	s_nop 0
	global_load_lds_dwordx4 v153, s[4:5]
	s_movk_i32 s4, 0x3c0
	s_waitcnt vmcnt(8)
	s_barrier
	v_and_b32_e32 v1, 15, v0
	v_or_b32_e32 v2, s64, v1
	v_lshlrev_b32_e32 v4, 6, v2
	v_and_b32_e32 v5, 48, v0
	v_ashrrev_i32_e32 v3, 6, v0
	v_lshlrev_b32_e32 v2, 2, v2
	v_and_or_b32 v4, v4, s4, v5
	v_readlane_b32 s4, v254, 19
	v_and_b32_e32 v2, 32, v2
	v_lshlrev_b32_e32 v0, 2, v0
	v_lshl_add_u32 v6, v3, 10, s4
	v_readlane_b32 s4, v254, 21
	s_waitcnt vmcnt(6)
	v_bitop3_b32 v2, v4, v6, v2 bitop3:0xde
	v_lshl_or_b32 v1, v1, 6, v5
	v_add_lshl_u32 v3, v3, s4, 10
	v_and_b32_e32 v0, 32, v0
	v_bitop3_b32 v154, v1, v3, v0 bitop3:0xde
	s_mov_b32 s57, 0
	v_add_u32_e32 v155, 0, v2
	s_barrier
	s_branch .LBB0_597

.LBB0_666:
	s_add_u32 s65, s20, 0x32800000
	s_addc_u32 s70, s21, 0
	s_add_u32 s71, s16, 0x33400000
	s_addc_u32 s78, s17, 0
	s_add_u32 s8, s8, 0x34000000
	s_addc_u32 s9, s9, 0
	s_add_u32 s80, s14, 0x2f800000
	s_addc_u32 s81, s15, 0
	s_add_u32 s10, s10, 0x200000
	s_addc_u32 s11, s11, 0
	s_add_u32 s4, s30, 0x80
	s_addc_u32 s5, s31, 0
	s_add_i32 m0, s48, 0x18000
	s_nop 0
	global_load_lds_dwordx4 v147, s[4:5]
	s_add_i32 m0, s48, 0x1a000
	s_nop 0
	global_load_lds_dwordx4 v149, s[4:5]
	s_add_u32 s4, s28, 0x80
	s_addc_u32 s5, s29, 0
	s_add_i32 s82, s48, 0x8000
	s_mov_b32 m0, s82
	s_add_i32 s83, s48, 0xa000
	global_load_lds_dwordx4 v146, s[4:5]
	s_mov_b32 m0, s83
	s_nop 0
	global_load_lds_dwordx4 v148, s[4:5]
	s_add_u32 s4, s30, 0x80080
	s_addc_u32 s5, s31, 0
	s_add_i32 m0, s48, 0x1c000
	s_nop 0
	global_load_lds_dwordx4 v147, s[4:5]
	s_add_i32 m0, s48, 0x1e000
	s_nop 0
	global_load_lds_dwordx4 v149, s[4:5]
	s_movk_i32 s4, 0x3c0
	s_waitcnt vmcnt(8)
	s_barrier
	v_and_b32_e32 v2, 15, v0
	v_or_b32_e32 v3, s64, v2
	v_lshlrev_b32_e32 v4, 6, v3
	v_and_b32_e32 v5, 48, v0
	v_and_b32_e32 v1, 0xfffffc00, v1
	v_lshlrev_b32_e32 v3, 2, v3
	v_and_or_b32 v4, v4, s4, v5
	v_readlane_b32 s4, v254, 19
	v_and_b32_e32 v3, 32, v3
	v_lshlrev_b32_e32 v0, 2, v0
	v_add_u32_e32 v6, s4, v1
	v_readlane_b32 s4, v254, 26
	s_waitcnt vmcnt(6)
	v_bitop3_b32 v3, v4, v6, v3 bitop3:0xde
	v_lshl_or_b32 v2, v2, 6, v5
	v_add_u32_e32 v1, s4, v1
	v_and_b32_e32 v0, 32, v0
	v_bitop3_b32 v150, v2, v1, v0 bitop3:0xde
	s_mov_b32 s72, 0
	v_add_u32_e32 v151, 0, v3
	s_barrier
	s_branch .LBB0_669

.LBB0_774:
	s_mul_i32 s4, s84, 0x1800
	s_add_u32 s4, s14, s4
	s_addc_u32 s5, s15, 0
	s_add_u32 s74, s4, 0x34800000
	s_addc_u32 s78, s5, 0
	s_add_u32 s4, s10, 0x38000000
	s_addc_u32 s5, s11, 0
	s_sub_u32 s4, s4, s74
	s_subb_u32 s5, s5, s78
	s_ashr_i64 s[10:11], s[4:5], 1
	s_add_u32 s12, s12, 0x2f800000
	s_addc_u32 s13, s13, 0
	s_add_u32 s4, s30, 0x80
	s_addc_u32 s5, s31, 0
	s_add_i32 m0, s27, 0x18000
	s_nop 0
	global_load_lds_dwordx4 v133, s[4:5]
	s_add_i32 m0, s27, 0x1a000
	s_nop 0
	global_load_lds_dwordx4 v135, s[4:5]
	s_add_u32 s4, s28, 0x80
	s_addc_u32 s5, s29, 0
	s_add_i32 s80, s27, 0x8000
	s_mov_b32 m0, s80
	s_add_i32 s81, s27, 0xa000
	global_load_lds_dwordx4 v132, s[4:5]
	s_mov_b32 m0, s81
	s_nop 0
	global_load_lds_dwordx4 v134, s[4:5]
	s_add_u32 s4, s30, 0x20080
	s_addc_u32 s5, s31, 0
	s_add_i32 m0, s27, 0x1c000
	s_nop 0
	global_load_lds_dwordx4 v133, s[4:5]
	s_add_i32 m0, s27, 0x1e000
	s_nop 0
	global_load_lds_dwordx4 v135, s[4:5]
	s_movk_i32 s4, 0x3c0
	s_waitcnt vmcnt(8)
	s_barrier
	v_cndmask_b32_e64 v1, 0, 1, s[8:9]
	s_nop 0
	v_readfirstlane_b32 s25, v1
	v_and_b32_e32 v1, 15, v0
	v_or_b32_e32 v2, s64, v1
	v_lshlrev_b32_e32 v4, 6, v2
	v_and_b32_e32 v5, 48, v0
	v_ashrrev_i32_e32 v3, 6, v0
	v_and_or_b32 v4, v4, s4, v5
	v_readlane_b32 s4, v254, 19
	v_lshlrev_b32_e32 v2, 2, v2
	v_and_b32_e32 v2, 32, v2
	v_lshl_add_u32 v6, v3, 10, s4
	v_readlane_b32 s4, v254, 21
	v_lshlrev_b32_e32 v0, 2, v0
	s_waitcnt vmcnt(6)
	v_bitop3_b32 v2, v4, v6, v2 bitop3:0xde
	v_lshl_or_b32 v1, v1, 6, v5
	v_add_lshl_u32 v3, v3, s4, 10
	v_and_b32_e32 v0, 32, v0
	v_bitop3_b32 v136, v1, v3, v0 bitop3:0xde
	s_mov_b32 s82, 0
	v_add_u32_e32 v137, 0, v2
	s_barrier
	s_branch .LBB0_777

.LBB0_1040:
	s_add_u32 s14, s14, 0x15300000
	s_addc_u32 s15, s15, 0
	s_lshl_b32 s44, s85, 12
	s_lshl_b64 s[4:5], s[44:45], 2
	s_add_u32 s4, s22, s4
	s_addc_u32 s5, s23, s5
	s_add_u32 s44, s4, 0x10000
	s_addc_u32 s49, s5, 0
	s_add_u32 s16, s16, 0x8000
	s_addc_u32 s17, s17, 0
	s_add_u32 s20, s20, 0x28100000
	s_addc_u32 s21, s21, 0
	v_readlane_b32 s28, v254, 62
	v_readlane_b32 s4, v255, 3
	v_readlane_b32 s29, v254, 63
	s_add_u32 s22, s28, 0x4000
	v_readlane_b32 s5, v255, 4
	s_addc_u32 s23, s29, 0
	s_lshl_b64 s[4:5], s[4:5], 2
	s_add_u32 s24, s24, s4
	s_addc_u32 s25, s25, s5
	s_add_u32 s26, s28, 0x8000
	s_addc_u32 s27, s29, 0
	s_add_u32 s28, s28, 0x6000
	s_addc_u32 s29, s29, 0
	s_add_u32 s30, s30, 0x2d100000
	s_addc_u32 s31, s31, 0
	s_add_u32 s4, s8, 0x80
	s_addc_u32 s5, s9, 0
	s_add_i32 m0, s92, 0x18000
	s_nop 0
	global_load_lds_dwordx4 v181, s[4:5]
	s_add_i32 m0, s92, 0x1a000
	s_nop 0
	global_load_lds_dwordx4 v183, s[4:5]
	s_add_u32 s4, s12, 0x80
	s_addc_u32 s5, s13, 0
	s_add_i32 s81, s92, 0x8000
	s_mov_b32 m0, s81
	s_add_i32 s70, s92, 0xa000
	global_load_lds_dwordx4 v179, s[4:5]
	s_mov_b32 m0, s70
	s_nop 0
	global_load_lds_dwordx4 v182, s[4:5]
	s_add_u32 s4, s34, 0x80
	s_addc_u32 s5, s35, 0
	s_add_i32 m0, s92, 0x1c000
	s_nop 0
	global_load_lds_dwordx4 v181, s[4:5]
	s_add_i32 m0, s92, 0x1e000
	s_nop 0
	global_load_lds_dwordx4 v183, s[4:5]
	s_movk_i32 s4, 0x3c0
	s_waitcnt vmcnt(8)
	s_barrier
	v_and_b32_e32 v2, 15, v0
	v_or_b32_e32 v3, s64, v2
	v_lshlrev_b32_e32 v4, 6, v3
	v_and_b32_e32 v5, 48, v0
	v_and_b32_e32 v1, 0xfffffc00, v1
	v_lshlrev_b32_e32 v3, 2, v3
	v_and_or_b32 v4, v4, s4, v5
	v_readlane_b32 s4, v254, 19
	v_and_b32_e32 v3, 32, v3
	v_lshlrev_b32_e32 v0, 2, v0
	v_add_u32_e32 v6, s4, v1
	v_readlane_b32 s4, v254, 26
	s_waitcnt vmcnt(6)
	v_bitop3_b32 v3, v4, v6, v3 bitop3:0xde
	v_lshl_or_b32 v2, v2, 6, v5
	v_add_u32_e32 v1, s4, v1
	v_and_b32_e32 v0, 32, v0
	v_bitop3_b32 v184, v2, v1, v0 bitop3:0xde
	s_mov_b32 s71, 0
	v_add_u32_e32 v185, 0, v3
	s_barrier
	s_branch .LBB0_1043

.LBB0_1117:
	s_add_u32 s10, s8, 0x54c00000
	s_addc_u32 s11, s9, 0
	v_readlane_b32 s4, v255, 1
	v_readlane_b32 s5, v255, 2
	s_add_u32 s12, s4, 0x4000
	s_addc_u32 s13, s5, 0
	s_add_u32 s4, s34, 0x80
	s_addc_u32 s5, s35, 0
	s_add_i32 m0, s27, 0x18000
	s_nop 0
	global_load_lds_dwordx4 v152, s[4:5]
	s_add_i32 m0, s27, 0x1a000
	s_nop 0
	global_load_lds_dwordx4 v153, s[4:5]
	s_add_u32 s4, s36, 0x80
	s_addc_u32 s5, s37, 0
	s_add_i32 s47, s27, 0x8000
	s_mov_b32 m0, s47
	s_add_i32 s48, s27, 0xa000
	global_load_lds_dwordx4 v151, s[4:5]
	s_mov_b32 m0, s48
	s_nop 0
	global_load_lds_dwordx4 v150, s[4:5]
	s_add_u32 s4, s14, 0x80
	s_addc_u32 s5, s15, 0
	s_add_i32 m0, s27, 0x1c000
	s_nop 0
	global_load_lds_dwordx4 v152, s[4:5]
	s_add_i32 m0, s27, 0x1e000
	s_nop 0
	global_load_lds_dwordx4 v153, s[4:5]
	s_movk_i32 s4, 0x3c0
	s_waitcnt vmcnt(8)
	s_barrier
	v_and_b32_e32 v1, 15, v0
	v_or_b32_e32 v2, s64, v1
	v_lshlrev_b32_e32 v4, 6, v2
	v_and_b32_e32 v5, 48, v0
	v_ashrrev_i32_e32 v3, 6, v0
	v_lshlrev_b32_e32 v2, 2, v2
	v_and_or_b32 v4, v4, s4, v5
	v_readlane_b32 s4, v254, 19
	v_and_b32_e32 v2, 32, v2
	v_lshlrev_b32_e32 v0, 2, v0
	v_lshl_add_u32 v6, v3, 10, s4
	v_readlane_b32 s4, v254, 21
	s_waitcnt vmcnt(6)
	v_bitop3_b32 v2, v4, v6, v2 bitop3:0xde
	v_lshl_or_b32 v1, v1, 6, v5
	v_add_lshl_u32 v3, v3, s4, 10
	v_and_b32_e32 v0, 32, v0
	v_bitop3_b32 v154, v1, v3, v0 bitop3:0xde
	s_mov_b32 s49, 0
	v_add_u32_e32 v155, 0, v2
	s_barrier
	s_branch .LBB0_1120

.LBB0_1243:
	s_mul_i32 s9, s84, 0x2c00
	s_add_u32 s9, s22, s9
	s_addc_u32 s22, s23, 0
	s_add_u32 s81, s9, 0x4a800000
	s_addc_u32 s82, s22, 0
	v_readlane_b32 s22, v255, 3
	v_readlane_b32 s23, v255, 4
	s_lshl_b64 s[22:23], s[22:23], 2
	s_add_u32 s9, s16, s22
	s_addc_u32 s22, s17, s23
	s_add_u32 s16, s9, 0x15200000
	s_addc_u32 s17, s22, 0
	s_lshr_b32 s23, s84, 6
	s_mul_i32 s23, s23, 0xb000
	s_add_u32 s20, s20, s23
	s_addc_u32 s21, s21, 0
	s_add_u32 s83, s20, 0x14a00000
	s_addc_u32 s84, s21, 0
	s_add_u32 s20, s9, 0x15221000
	s_addc_u32 s21, s22, 0
	s_add_u32 s22, s34, 0x80
	s_addc_u32 s23, s35, 0
	s_add_i32 m0, s15, 0x18000
	s_nop 0
	global_load_lds_dwordx4 v193, s[22:23]
	s_add_i32 m0, s15, 0x1a000
	s_nop 0
	global_load_lds_dwordx4 v195, s[22:23]
	s_add_u32 s22, s10, 0x80
	s_addc_u32 s23, s11, 0
	s_add_i32 s85, s15, 0x8000
	s_mov_b32 m0, s85
	s_add_i32 s86, s15, 0xa000
	global_load_lds_dwordx4 v192, s[22:23]
	s_mov_b32 m0, s86
	s_nop 0
	global_load_lds_dwordx4 v194, s[22:23]
	s_add_u32 s22, s34, 0x80080
	s_addc_u32 s23, s35, 0
	s_add_i32 m0, s15, 0x1c000
	s_nop 0
	global_load_lds_dwordx4 v193, s[22:23]
	s_add_i32 m0, s15, 0x1e000
	s_nop 0
	global_load_lds_dwordx4 v195, s[22:23]
	s_waitcnt vmcnt(8)
	s_barrier
	v_and_b32_e32 v2, 15, v0
	v_or_b32_e32 v3, s64, v2
	v_lshlrev_b32_e32 v5, 6, v3
	v_and_b32_e32 v6, 48, v0
	s_movk_i32 s9, 0x3c0
	v_ashrrev_i32_e32 v4, 6, v0
	v_and_or_b32 v5, v5, s9, v6
	v_readlane_b32 s9, v254, 19
	v_lshlrev_b32_e32 v0, 2, v0
	v_lshl_or_b32 v2, v2, 6, v6
	v_lshl_add_u32 v7, v4, 10, s9
	v_readlane_b32 s9, v254, 21
	v_and_b32_e32 v0, 32, v0
	v_mul_f32_e32 v1, 0x4f7ffffe, v1
	v_add_lshl_u32 v4, v4, s9, 10
	v_bitop3_b32 v196, v2, v4, v0 bitop3:0xde
	v_cvt_f32_u32_e32 v0, s56
	v_cvt_u32_f32_e32 v1, v1
	s_lshl_b32 s5, s5, 2
	v_readlane_b32 s9, v254, 44
	v_rcp_iflag_f32_e32 v0, v0
	s_lshl_b32 s4, s4, 2
	s_add_i32 s87, s9, s5
	s_add_i32 s89, s9, s4
	v_mul_f32_e32 v0, 0x4f7ffffe, v0
	v_cvt_u32_f32_e32 v0, v0
	s_sub_i32 s4, 0, s2
	v_readfirstlane_b32 s5, v1
	s_mul_i32 s4, s4, s5
	s_mul_hi_u32 s4, s5, s4
	v_lshlrev_b32_e32 v3, 2, v3
	s_add_i32 s93, s5, s4
	s_sub_i32 s4, 0, s56
	v_readfirstlane_b32 s5, v0
	v_and_b32_e32 v3, 32, v3
	s_waitcnt vmcnt(6)
	s_mul_i32 s4, s4, s5
	v_bitop3_b32 v3, v5, v7, v3 bitop3:0xde
	s_mul_hi_u32 s4, s5, s4
	s_mov_b32 s92, 0
	s_add_i32 s74, s5, s4
	v_add_u32_e32 v200, 0, v3
	s_barrier
	s_branch .LBB0_1246

.LBB0_1276:
	s_add_u32 s65, s16, 0x3f585000
	s_addc_u32 s69, s17, 0
	s_add_u32 s4, s10, 0x58600000
	s_addc_u32 s5, s11, 0
	s_waitcnt lgkmcnt(0)
	s_add_u32 s10, s12, 0x3f585000
	s_addc_u32 s11, s13, 0
	s_sub_u32 s4, s4, s10
	s_subb_u32 s5, s5, s11
	s_ashr_i64 s[12:13], s[4:5], 1
	s_add_u32 s4, s34, 0x80
	s_addc_u32 s5, s35, 0
	s_add_i32 m0, s27, 0x18000
	s_nop 0
	global_load_lds_dwordx4 v132, s[4:5]
	s_add_i32 m0, s27, 0x1a000
	s_nop 0
	global_load_lds_dwordx4 v130, s[4:5]
	s_add_u32 s4, s36, 0x80
	s_addc_u32 s5, s37, 0
	s_add_i32 s70, s27, 0x8000
	s_mov_b32 m0, s70
	s_add_i32 s71, s27, 0xa000
	global_load_lds_dwordx4 v133, s[4:5]
	s_mov_b32 m0, s71
	s_nop 0
	global_load_lds_dwordx4 v131, s[4:5]
	s_add_u32 s4, s20, 0x80
	s_addc_u32 s5, s21, 0
	s_add_i32 m0, s27, 0x1c000
	s_nop 0
	global_load_lds_dwordx4 v132, s[4:5]
	s_add_i32 m0, s27, 0x1e000
	s_nop 0
	global_load_lds_dwordx4 v130, s[4:5]
	s_movk_i32 s4, 0x3c0
	s_waitcnt vmcnt(8)
	s_barrier
	v_and_b32_e32 v1, 15, v0
	v_or_b32_e32 v2, s64, v1
	v_lshlrev_b32_e32 v4, 6, v2
	v_and_b32_e32 v5, 48, v0
	v_ashrrev_i32_e32 v3, 6, v0
	v_lshlrev_b32_e32 v2, 2, v2
	v_and_or_b32 v4, v4, s4, v5
	v_readlane_b32 s4, v254, 19
	v_and_b32_e32 v2, 32, v2
	v_lshlrev_b32_e32 v0, 2, v0
	v_lshl_add_u32 v6, v3, 10, s4
	v_readlane_b32 s4, v254, 21
	s_waitcnt vmcnt(6)
	v_bitop3_b32 v2, v4, v6, v2 bitop3:0xde
	v_lshl_or_b32 v1, v1, 6, v5
	v_add_lshl_u32 v3, v3, s4, 10
	v_and_b32_e32 v0, 32, v0
	v_bitop3_b32 v134, v1, v3, v0 bitop3:0xde
	s_mov_b32 s72, 0
	v_add_u32_e32 v135, 0, v2
	s_barrier
	s_branch .LBB0_1279

.LBB0_1411:
	s_add_u32 s30, s30, 0x2000
	s_addc_u32 s31, s31, 0
	s_waitcnt lgkmcnt(0)
	s_add_u32 s34, s34, 0x15300000
	v_readlane_b32 s4, v255, 0
	s_addc_u32 s35, s35, 0
	s_lshl_b32 s44, s4, 11
	s_lshl_b64 s[4:5], s[44:45], 2
	s_add_u32 s4, s16, s4
	s_addc_u32 s5, s17, s5
	s_add_u32 s44, s4, 0x10000
	s_addc_u32 s82, s5, 0
	s_add_u32 s4, s12, 0x8000
	s_addc_u32 s5, s13, 0
	v_writelane_b32 v255, s4, 12
	s_add_u32 s38, s10, 0x28100000
	s_addc_u32 s39, s11, 0
	v_writelane_b32 v255, s5, 13
	v_readlane_b32 s4, v254, 62
	v_readlane_b32 s5, v254, 63
	s_add_u32 s40, s4, 0xa000
	s_addc_u32 s41, s5, 0
	s_add_u32 s4, s74, 0x80
	s_addc_u32 s5, s75, 0
	s_add_i32 m0, s2, 0x18000
	s_nop 0
	global_load_lds_dwordx4 v169, s[4:5]
	s_add_i32 m0, s2, 0x1a000
	s_nop 0
	global_load_lds_dwordx4 v171, s[4:5]
	s_add_u32 s4, s80, 0x80
	s_addc_u32 s5, s81, 0
	s_add_i32 s19, s2, 0x8000
	s_mov_b32 m0, s19
	s_add_i32 s89, s2, 0xa000
	global_load_lds_dwordx4 v168, s[4:5]
	s_mov_b32 m0, s89
	s_nop 0
	global_load_lds_dwordx4 v170, s[4:5]
	s_add_u32 s4, s46, 0x80
	s_addc_u32 s5, s47, 0
	s_add_i32 m0, s2, 0x1c000
	s_nop 0
	global_load_lds_dwordx4 v169, s[4:5]
	s_add_i32 m0, s2, 0x1e000
	s_nop 0
	global_load_lds_dwordx4 v171, s[4:5]
	s_movk_i32 s4, 0x3c0
	s_waitcnt vmcnt(8)
	s_barrier
	v_and_b32_e32 v2, 15, v0
	v_or_b32_e32 v3, s64, v2
	v_lshlrev_b32_e32 v4, 6, v3
	v_and_b32_e32 v5, 48, v0
	v_and_b32_e32 v1, 0xfffffc00, v1
	v_lshlrev_b32_e32 v3, 2, v3
	v_and_or_b32 v4, v4, s4, v5
	v_readlane_b32 s4, v254, 19
	v_and_b32_e32 v3, 32, v3
	v_lshlrev_b32_e32 v0, 2, v0
	v_add_u32_e32 v6, s4, v1
	v_readlane_b32 s4, v254, 26
	s_waitcnt vmcnt(6)
	v_bitop3_b32 v3, v4, v6, v3 bitop3:0xde
	v_lshl_or_b32 v2, v2, 6, v5
	v_add_u32_e32 v1, s4, v1
	v_and_b32_e32 v0, 32, v0
	s_cmp_lg_u64 s[26:27], 0
	v_bitop3_b32 v172, v2, v1, v0 bitop3:0xde
	s_mov_b32 s36, 0
	s_cselect_b64 s[46:47], -1, 0
	v_add_u32_e32 v173, 0, v3
	s_barrier
	s_branch .LBB0_1414

.LBB0_1569:
	s_add_u32 s8, s6, 0x54c00000
	s_addc_u32 s9, s7, 0
	v_readlane_b32 s6, v255, 1
	v_readlane_b32 s7, v255, 2
	s_add_u32 s10, s6, 0xa000
	s_addc_u32 s11, s7, 0
	s_add_u32 s6, s22, 0x80
	s_addc_u32 s7, s23, 0
	s_add_i32 m0, s31, 0x18000
	s_nop 0
	global_load_lds_dwordx4 v152, s[6:7]
	s_add_i32 m0, s31, 0x1a000
	s_nop 0
	global_load_lds_dwordx4 v153, s[6:7]
	s_add_u32 s6, s24, 0x80
	s_addc_u32 s7, s25, 0
	s_add_i32 s37, s31, 0x8000
	s_mov_b32 m0, s37
	s_add_i32 s38, s31, 0xa000
	global_load_lds_dwordx4 v151, s[6:7]
	s_mov_b32 m0, s38
	s_nop 0
	global_load_lds_dwordx4 v150, s[6:7]
	s_add_u32 s6, s12, 0x80
	s_addc_u32 s7, s13, 0
	s_add_i32 m0, s31, 0x1c000
	s_nop 0
	global_load_lds_dwordx4 v152, s[6:7]
	s_add_i32 m0, s31, 0x1e000
	s_nop 0
	global_load_lds_dwordx4 v153, s[6:7]
	s_movk_i32 s6, 0x3c0
	s_waitcnt vmcnt(8)
	s_barrier
	v_and_b32_e32 v1, 15, v0
	v_or_b32_e32 v2, s64, v1
	v_lshlrev_b32_e32 v4, 6, v2
	v_and_b32_e32 v5, 48, v0
	v_ashrrev_i32_e32 v3, 6, v0
	v_lshlrev_b32_e32 v2, 2, v2
	v_and_or_b32 v4, v4, s6, v5
	v_readlane_b32 s6, v254, 19
	v_and_b32_e32 v2, 32, v2
	v_lshlrev_b32_e32 v0, 2, v0
	v_lshl_add_u32 v6, v3, 10, s6
	v_readlane_b32 s6, v254, 21
	s_waitcnt vmcnt(6)
	v_bitop3_b32 v2, v4, v6, v2 bitop3:0xde
	v_lshl_or_b32 v1, v1, 6, v5
	v_add_lshl_u32 v3, v3, s6, 10
	v_and_b32_e32 v0, 32, v0
	v_bitop3_b32 v154, v1, v3, v0 bitop3:0xde
	s_mov_b32 s39, 0
	v_add_u32_e32 v155, 0, v2
	s_barrier
	s_branch .LBB0_1572
